# v19: v18 + phase-0 x-row loop keeps two rows in flight per wave (body emitted twice with alternating landing registers, counted vmcnt)
# baseline (speedup 1.0000x reference)
.LBB0_772:
	s_or_b64 exec, exec, s[10:11]
	v_readlane_b32 s4, v251, 26
	v_readlane_b32 s5, v251, 27
	s_and_b64 vcc, exec, s[4:5]
	s_waitcnt lgkmcnt(0)
	s_barrier
	s_cbranch_vccz .LBB0_779
	v_readlane_b32 s16, v255, 34
	v_readlane_b32 s17, v255, 35
	s_load_dwordx2 s[4:5], s[16:17], 0x78
	s_load_dwordx2 s[10:11], s[16:17], 0x20
	s_nop 0
	s_load_dwordx2 s[16:17], s[16:17], 0x0
	v_and_b32_e32 v19, 7, v227
	v_lshlrev_b32_e32 v0, 2, v19
	v_mov_b32_e32 v21, v1
	s_waitcnt lgkmcnt(0)
	global_load_dword v0, v0, s[4:5]
	s_nop 0
	global_load_dwordx4 v[2:5], v22, s[10:11] offset:3072
	global_load_dwordx4 v[6:9], v22, s[10:11] offset:2048
	global_load_dwordx4 v[10:13], v22, s[10:11] offset:1024
	global_load_dwordx4 v[14:17], v22, s[10:11]
	v_readlane_b32 s4, v254, 33
	v_readlane_b32 s5, v254, 34
	s_add_u32 s4, s16, s4
	s_addc_u32 s5, s17, s5
	s_nop 2
	global_load_dwordx4 v[34:37], v22, s[4:5] offset:3072
	global_load_dwordx4 v[38:41], v22, s[4:5] offset:2048
	global_load_dwordx4 v[42:45], v22, s[4:5] offset:1024
	global_load_dwordx4 v[46:49], v22, s[4:5]
	v_readlane_b32 s4, v255, 38
	v_readlane_b32 s5, v255, 39
	s_add_u32 s10, s4, 0xeb00000
	s_addc_u32 s11, s5, 0
	v_readlane_b32 s4, v254, 27
	v_readlane_b32 s5, v254, 28
	v_mov_b32_e32 v23, v1
	v_cmp_eq_u32_e64 s[48:49], 0, v19
	v_lshl_add_u64 v[52:53], s[4:5], 0, v[20:21]
	v_readlane_b32 s4, v254, 15
	v_cmp_eq_u32_e64 s[50:51], 1, v19
	v_cmp_eq_u32_e64 s[52:53], 2, v19
	v_cmp_eq_u32_e64 s[54:55], 3, v19
	v_cmp_eq_u32_e64 s[56:57], 4, v19
	v_cmp_eq_u32_e64 s[58:59], 5, v19
	v_cmp_eq_u32_e64 s[60:61], 6, v19
	v_cmp_eq_u32_e64 s[62:63], 7, v19
	v_mov_b32_e32 v19, v1
	v_readlane_b32 s5, v254, 16
	v_lshl_add_u64 v[50:51], s[16:17], 0, v[22:23]
	v_lshlrev_b32_e32 v22, 5, v226
	v_lshl_add_u64 v[54:55], s[4:5], 0, v[18:19]
	v_readlane_b32 s4, v254, 23
	s_mov_b32 s9, 0x800000
	v_cmp_gt_u32_e64 s[42:43], 16, v226
	v_cmp_eq_u32_e64 s[44:45], 0, v226
	v_cmp_gt_u32_e64 s[46:47], 8, v226
	v_add_u32_e32 v58, 0, v22
	s_mov_b32 s1, s4
	v_readlane_b32 s5, v254, 24
	v_readlane_b32 s22, v254, 49
	s_nop 0
	s_add_i32 s22, s4, s22
	s_ashr_i32 s23, s22, 31
	s_lshl_b64 s[22:23], s[22:23], 12
	v_lshl_add_u64 v[128:129], v[50:51], 0, s[22:23]
	global_load_dwordx4 v[18:21], v[128:129], off
	global_load_dwordx4 v[22:25], v[128:129], off offset:1024
	global_load_dwordx4 v[26:29], v[128:129], off offset:2048
	global_load_dwordx4 v[30:33], v[128:129], off offset:3072
	s_waitcnt vmcnt(0)
	s_branch .LBB0_775
.LBB0_774:
	s_or_b64 exec, exec, s[28:29]
	v_readlane_b32 s22, v254, 51
	s_waitcnt vmcnt(10)
	v_readlane_b32 s23, v254, 52
	v_mov_b64_e32 v[36:37], v[32:33]
	v_mov_b64_e32 v[40:41], v[28:29]
	v_mov_b64_e32 v[44:45], v[24:25]
	v_mov_b64_e32 v[48:49], v[20:21]
	v_lshl_add_u64 v[52:53], v[52:53], 0, s[22:23]
	v_lshl_add_u64 v[54:55], v[54:55], 0, s[64:65]
	s_and_b64 vcc, exec, s[16:17]
	v_mov_b64_e32 v[34:35], v[30:31]
	v_mov_b64_e32 v[38:39], v[26:27]
	v_mov_b64_e32 v[42:43], v[22:23]
	v_mov_b64_e32 v[46:47], v[18:19]
	s_mov_b32 s1, s4
	s_cbranch_vccnz .LBB0_779
.Lx2_775:
	v_pk_mul_f32 v[128:129], v[48:49], v[48:49]
	v_pk_mul_f32 v[130:131], v[46:47], v[46:47]
	v_cmp_lt_i32_e32 vcc, v250, v213
	v_pk_mov_b32 v[132:133], v[130:131], v[128:129] op_sel:[1,0]
	v_mov_b32_e32 v131, v129
	v_pk_add_f32 v[128:129], v[132:133], v[130:131]
	v_pk_mul_f32 v[130:131], v[44:45], v[44:45]
	v_pk_add_f32 v[128:129], v[128:129], v[128:129] op_sel_hi:[0,1]
	v_pk_mul_f32 v[132:133], v[42:43], v[42:43]
	v_mul_f32_e32 v128, v38, v38
	v_pk_mov_b32 v[134:135], v[132:133], v[130:131] op_sel:[1,0]
	v_mov_b32_e32 v133, v131
	v_pk_add_f32 v[130:131], v[134:135], v[132:133]
	v_pk_fma_f32 v[132:133], v[38:39], v[38:39], v[128:129] op_sel_hi:[1,1,0]
	v_mul_f32_e32 v128, v40, v40
	v_pk_add_f32 v[130:131], v[130:131], v[130:131] op_sel_hi:[0,1]
	v_pk_fma_f32 v[134:135], v[40:41], v[40:41], v[128:129] op_sel_hi:[1,1,0]
	v_mul_f32_e32 v132, v34, v34
	v_mul_f32_e32 v134, v35, v35
	v_mul_f32_e32 v130, v36, v36
	v_mul_f32_e32 v128, v37, v37
	v_pk_add_f32 v[132:133], v[132:133], v[134:135]
	v_pk_add_f32 v[128:129], v[130:131], v[128:129]
	v_readlane_b32 s4, v254, 49
	v_pk_add_f32 v[128:129], v[132:133], v[128:129]
	s_add_i32 s4, s1, s4
	v_add_f32_e32 v128, v128, v129
	v_cndmask_b32_e32 v129, v211, v250, vcc
	v_lshlrev_b32_e32 v62, 2, v129
	ds_bpermute_b32 v129, v62, v128
	v_cmp_lt_i32_e32 vcc, v221, v213
	s_cmpk_gt_i32 s4, 0x3fff
	s_cselect_b64 s[16:17], -1, 0
	v_readlane_b32 s22, v254, 49
	s_nop 0
	s_add_i32 s22, s4, s22
	s_cmpk_lt_i32 s22, 0x4000
	s_waitcnt lgkmcnt(0)
	v_add_f32_e32 v128, v128, v129
	v_cndmask_b32_e32 v129, v211, v221, vcc
	v_lshlrev_b32_e32 v61, 2, v129
	ds_bpermute_b32 v129, v61, v128
	v_cmp_lt_i32_e32 vcc, v212, v213
	s_cselect_b32 s22, s22, s1
	s_ashr_i32 s23, s22, 31
	s_lshl_b64 s[22:23], s[22:23], 12
	s_waitcnt lgkmcnt(0)
	v_add_f32_e32 v128, v128, v129
	v_cndmask_b32_e32 v129, v211, v212, vcc
	v_lshlrev_b32_e32 v60, 2, v129
	ds_bpermute_b32 v129, v60, v128
	v_cmp_lt_i32_e32 vcc, v210, v213
	v_lshl_add_u64 v[140:141], v[50:51], 0, s[22:23]
	s_mov_b64 s[22:23], 0x400
	v_lshl_add_u64 v[132:133], v[140:141], 0, s[22:23]
	s_waitcnt lgkmcnt(0)
	v_add_f32_e32 v128, v128, v129
	v_cndmask_b32_e32 v129, v211, v210, vcc
	v_lshlrev_b32_e32 v63, 2, v129
	ds_bpermute_b32 v129, v63, v128
	v_cmp_lt_i32_e32 vcc, v218, v213
	s_mov_b64 s[22:23], 0x800
	v_add_u32_e32 v70, 0x12000, v58
	v_readlane_b32 s5, v254, 50
	s_waitcnt lgkmcnt(0)
	v_add_f32_e32 v136, v128, v129
	v_cndmask_b32_e32 v128, v211, v218, vcc
	v_lshlrev_b32_e32 v64, 2, v128
	ds_bpermute_b32 v137, v64, v136
	v_cmp_lt_i32_e32 vcc, v219, v213
	global_load_dwordx4 v[18:21], v[140:141], off
	global_load_dwordx4 v[22:25], v[132:133], off
	s_brev_b32 s5, 32
	s_waitcnt lgkmcnt(0)
	v_add_f32_e32 v56, v136, v137
	v_cndmask_b32_e32 v136, v211, v219, vcc
	v_lshlrev_b32_e32 v65, 2, v136
	ds_bpermute_b32 v57, v65, v56
	v_lshl_add_u64 v[136:137], v[140:141], 0, s[22:23]
	s_mov_b64 s[22:23], 0xc00
	v_lshl_add_u64 v[140:141], v[140:141], 0, s[22:23]
	global_load_dwordx4 v[26:29], v[136:137], off
	global_load_dwordx4 v[30:33], v[140:141], off
	v_readlane_b32 s22, v255, 38
	ds_read_b128 v[66:69], v70
	ds_read_b128 v[70:73], v70 offset:16
	v_readlane_b32 s23, v255, 39
	s_waitcnt lgkmcnt(2)
	v_add_f32_e32 v59, v56, v57
	v_cvt_pk_bf16_f32 v74, v46, v47
	v_lshl_add_u64 v[56:57], s[22:23], 0, v[54:55]
	v_add_co_u32_e32 v56, vcc, s5, v56
	v_cvt_pk_bf16_f32 v75, v48, v49
	s_nop 0
	v_addc_co_u32_e32 v57, vcc, 0, v57, vcc
	v_mul_f32_e32 v46, v14, v46
	global_store_dwordx2 v[56:57], v[74:75], off
	s_waitcnt lgkmcnt(0)
	v_fma_f32 v79, v46, v70, 0
	v_add_u32_e32 v70, 0x12800, v58
	v_fma_f32 v78, v46, v66, 0
	v_fma_f32 v80, v46, v67, 0
	v_fma_f32 v82, v46, v68, 0
	v_fma_f32 v83, v46, v69, 0
	ds_read_b128 v[66:69], v70
	ds_read_b128 v[74:77], v70 offset:16
	v_fma_f32 v81, v46, v71, 0
	v_fma_f32 v84, v46, v72, 0
	v_fma_f32 v85, v46, v73, 0
	v_mul_f32_e32 v46, v15, v47
	v_add_u32_e32 v47, 0x13000, v58
	s_waitcnt lgkmcnt(1)
	v_fmac_f32_e32 v78, v46, v66
	v_fmac_f32_e32 v80, v46, v67
	v_fmac_f32_e32 v82, v46, v68
	v_fmac_f32_e32 v83, v46, v69
	ds_read_b128 v[66:69], v47
	ds_read_b128 v[70:73], v47 offset:16
	s_waitcnt lgkmcnt(2)
	v_fmac_f32_e32 v79, v46, v74
	v_fmac_f32_e32 v81, v46, v75
	v_fmac_f32_e32 v84, v46, v76
	v_fmac_f32_e32 v85, v46, v77
	v_mul_f32_e32 v46, v16, v48
	v_add_u32_e32 v47, 0x13800, v58
	s_waitcnt lgkmcnt(1)
	v_fmac_f32_e32 v78, v46, v66
	v_fmac_f32_e32 v80, v46, v67
	v_fmac_f32_e32 v82, v46, v68
	v_fmac_f32_e32 v83, v46, v69
	ds_read_b128 v[66:69], v47
	ds_read_b128 v[74:77], v47 offset:16
	s_waitcnt lgkmcnt(2)
	v_fmac_f32_e32 v79, v46, v70
	v_fmac_f32_e32 v81, v46, v71
	v_fmac_f32_e32 v84, v46, v72
	v_fmac_f32_e32 v85, v46, v73
	v_mul_f32_e32 v46, v17, v49
	s_waitcnt lgkmcnt(1)
	v_fmac_f32_e32 v78, v46, v66
	v_add_u32_e32 v66, 0x14000, v58
	s_waitcnt lgkmcnt(0)
	v_fmac_f32_e32 v79, v46, v74
	v_fmac_f32_e32 v80, v46, v67
	v_fmac_f32_e32 v81, v46, v75
	v_fmac_f32_e32 v82, v46, v68
	v_fmac_f32_e32 v84, v46, v76
	v_fmac_f32_e32 v83, v46, v69
	v_fmac_f32_e32 v85, v46, v77
	ds_read_b128 v[46:49], v66
	ds_read_b128 v[66:69], v66 offset:16
	v_cvt_pk_bf16_f32 v70, v42, v43
	v_cvt_pk_bf16_f32 v71, v44, v45
	v_mul_f32_e32 v42, v10, v42
	global_store_dwordx2 v[56:57], v[70:71], off offset:512
	s_waitcnt lgkmcnt(1)
	v_fmac_f32_e32 v78, v42, v46
	v_add_u32_e32 v46, 0x14800, v58
	ds_read_b128 v[70:73], v46
	ds_read_b128 v[74:77], v46 offset:16
	s_waitcnt lgkmcnt(2)
	v_fmac_f32_e32 v79, v42, v66
	v_fmac_f32_e32 v80, v42, v47
	v_fmac_f32_e32 v81, v42, v67
	v_fmac_f32_e32 v82, v42, v48
	v_fmac_f32_e32 v84, v42, v68
	v_fmac_f32_e32 v83, v42, v49
	v_fmac_f32_e32 v85, v42, v69
	v_mul_f32_e32 v42, v11, v43
	v_add_u32_e32 v43, 0x15000, v58
	ds_read_b128 v[46:49], v43
	ds_read_b128 v[66:69], v43 offset:16
	v_add_u32_e32 v43, 0x15800, v58
	s_waitcnt lgkmcnt(3)
	v_fmac_f32_e32 v78, v42, v70
	s_waitcnt lgkmcnt(2)
	v_fmac_f32_e32 v79, v42, v74
	v_fmac_f32_e32 v80, v42, v71
	v_fmac_f32_e32 v81, v42, v75
	v_fmac_f32_e32 v82, v42, v72
	v_fmac_f32_e32 v84, v42, v76
	v_fmac_f32_e32 v83, v42, v73
	v_fmac_f32_e32 v85, v42, v77
	ds_read_b128 v[70:73], v43
	ds_read_b128 v[74:77], v43 offset:16
	v_mul_f32_e32 v42, v12, v44
	s_waitcnt lgkmcnt(3)
	v_fmac_f32_e32 v78, v42, v46
	s_waitcnt lgkmcnt(2)
	v_fmac_f32_e32 v79, v42, v66
	v_fmac_f32_e32 v80, v42, v47
	v_fmac_f32_e32 v81, v42, v67
	v_fmac_f32_e32 v82, v42, v48
	v_fmac_f32_e32 v84, v42, v68
	v_fmac_f32_e32 v83, v42, v49
	v_fmac_f32_e32 v85, v42, v69
	v_mul_f32_e32 v42, v13, v45
	s_waitcnt lgkmcnt(1)
	v_fmac_f32_e32 v78, v42, v70
	s_waitcnt lgkmcnt(0)
	v_fmac_f32_e32 v79, v42, v74
	v_fmac_f32_e32 v80, v42, v71
	v_fmac_f32_e32 v81, v42, v75
	v_fmac_f32_e32 v82, v42, v72
	v_fmac_f32_e32 v84, v42, v76
	v_fmac_f32_e32 v83, v42, v73
	v_fmac_f32_e32 v85, v42, v77
	v_add_u32_e32 v42, 0x16000, v58
	ds_read_b128 v[44:47], v42
	ds_read_b128 v[66:69], v42 offset:16
	v_cvt_pk_bf16_f32 v42, v38, v39
	v_mul_f32_e32 v38, v6, v38
	v_cvt_pk_bf16_f32 v43, v40, v41
	s_waitcnt lgkmcnt(1)
	v_fmac_f32_e32 v78, v38, v44
	v_add_u32_e32 v44, 0x16800, v58
	ds_read_b128 v[70:73], v44
	ds_read_b128 v[74:77], v44 offset:16
	s_waitcnt lgkmcnt(2)
	v_fmac_f32_e32 v79, v38, v66
	v_fmac_f32_e32 v80, v38, v45
	v_fmac_f32_e32 v81, v38, v67
	v_fmac_f32_e32 v82, v38, v46
	v_fmac_f32_e32 v84, v38, v68
	v_fmac_f32_e32 v83, v38, v47
	v_fmac_f32_e32 v85, v38, v69
	v_mul_f32_e32 v38, v7, v39
	v_add_u32_e32 v39, 0x17000, v58
	ds_read_b128 v[44:47], v39
	ds_read_b128 v[66:69], v39 offset:16
	v_add_u32_e32 v39, 0x17800, v58
	s_waitcnt lgkmcnt(3)
	v_fmac_f32_e32 v78, v38, v70
	s_waitcnt lgkmcnt(2)
	v_fmac_f32_e32 v79, v38, v74
	v_fmac_f32_e32 v80, v38, v71
	v_fmac_f32_e32 v81, v38, v75
	v_fmac_f32_e32 v82, v38, v72
	v_fmac_f32_e32 v84, v38, v76
	v_fmac_f32_e32 v83, v38, v73
	v_fmac_f32_e32 v85, v38, v77
	v_mul_f32_e32 v38, v8, v40
	ds_read_b128 v[70:73], v39
	ds_read_b128 v[74:77], v39 offset:16
	s_waitcnt lgkmcnt(3)
	v_fmac_f32_e32 v78, v38, v44
	v_add_u32_e32 v44, 0x18000, v58
	s_waitcnt lgkmcnt(2)
	v_fmac_f32_e32 v79, v38, v66
	v_fmac_f32_e32 v80, v38, v45
	v_fmac_f32_e32 v81, v38, v67
	v_fmac_f32_e32 v82, v38, v46
	v_fmac_f32_e32 v84, v38, v68
	v_fmac_f32_e32 v83, v38, v47
	v_fmac_f32_e32 v85, v38, v69
	v_mul_f32_e32 v48, v9, v41
	ds_read_b128 v[38:41], v44
	ds_read_b128 v[44:47], v44 offset:16
	s_waitcnt lgkmcnt(3)
	v_fmac_f32_e32 v78, v48, v70
	s_waitcnt lgkmcnt(2)
	v_fmac_f32_e32 v79, v48, v74
	v_fmac_f32_e32 v80, v48, v71
	v_fmac_f32_e32 v81, v48, v75
	v_fmac_f32_e32 v82, v48, v72
	v_fmac_f32_e32 v84, v48, v76
	v_fmac_f32_e32 v83, v48, v73
	v_fmac_f32_e32 v85, v48, v77
	v_mul_f32_e32 v48, v2, v34
	s_waitcnt lgkmcnt(1)
	v_fmac_f32_e32 v78, v48, v38
	v_add_u32_e32 v38, 0x18800, v58
	ds_read_b128 v[66:69], v38
	ds_read_b128 v[70:73], v38 offset:16
	s_waitcnt lgkmcnt(2)
	v_fmac_f32_e32 v79, v48, v44
	v_add_u32_e32 v44, 0x19000, v58
	v_fmac_f32_e32 v80, v48, v39
	v_fmac_f32_e32 v81, v48, v45
	v_fmac_f32_e32 v82, v48, v40
	v_fmac_f32_e32 v84, v48, v46
	v_fmac_f32_e32 v83, v48, v41
	v_fmac_f32_e32 v85, v48, v47
	ds_read_b128 v[38:41], v44
	ds_read_b128 v[44:47], v44 offset:16
	v_mul_f32_e32 v48, v3, v35
	s_waitcnt lgkmcnt(3)
	v_fmac_f32_e32 v78, v48, v66
	s_waitcnt lgkmcnt(2)
	v_fmac_f32_e32 v79, v48, v70
	v_fmac_f32_e32 v80, v48, v67
	v_fmac_f32_e32 v81, v48, v71
	v_fmac_f32_e32 v82, v48, v68
	v_fmac_f32_e32 v84, v48, v72
	v_fmac_f32_e32 v83, v48, v69
	v_fmac_f32_e32 v85, v48, v73
	v_mul_f32_e32 v48, v4, v36
	s_waitcnt lgkmcnt(1)
	v_fmac_f32_e32 v78, v48, v38
	v_add_u32_e32 v38, 0x19800, v58
	ds_read_b128 v[66:69], v38
	ds_read_b128 v[70:73], v38 offset:16
	v_mul_f32_e32 v38, v5, v37
	v_fmac_f32_e32 v80, v48, v39
	v_fmac_f32_e32 v82, v48, v40
	s_waitcnt lgkmcnt(1)
	v_fmac_f32_e32 v78, v38, v66
	ds_bpermute_b32 v39, v62, v78
	v_fmac_f32_e32 v80, v38, v67
	v_fmac_f32_e32 v83, v48, v41
	ds_bpermute_b32 v41, v62, v80
	v_fmac_f32_e32 v79, v48, v44
	s_waitcnt lgkmcnt(1)
	v_add_f32_e32 v39, v78, v39
	ds_bpermute_b32 v40, v61, v39
	v_fmac_f32_e32 v81, v48, v45
	s_waitcnt lgkmcnt(1)
	v_add_f32_e32 v41, v80, v41
	ds_bpermute_b32 v44, v61, v41
	v_fmac_f32_e32 v84, v48, v46
	s_waitcnt lgkmcnt(1)
	v_add_f32_e32 v39, v39, v40
	ds_bpermute_b32 v40, v60, v39
	v_fmac_f32_e32 v85, v48, v47
	v_fmac_f32_e32 v82, v38, v68
	s_waitcnt lgkmcnt(1)
	v_add_f32_e32 v41, v41, v44
	v_fmac_f32_e32 v79, v38, v70
	s_waitcnt lgkmcnt(0)
	v_add_f32_e32 v39, v39, v40
	v_fmac_f32_e32 v81, v38, v71
	v_fmac_f32_e32 v84, v38, v72
	v_fmac_f32_e32 v83, v38, v69
	ds_bpermute_b32 v40, v63, v39
	ds_bpermute_b32 v44, v60, v41
	v_fmac_f32_e32 v85, v38, v73
	ds_bpermute_b32 v38, v62, v82
	ds_bpermute_b32 v67, v62, v81
	s_waitcnt lgkmcnt(3)
	v_add_f32_e32 v39, v39, v40
	s_waitcnt lgkmcnt(2)
	v_add_f32_e32 v41, v41, v44
	ds_bpermute_b32 v40, v64, v39
	s_waitcnt lgkmcnt(2)
	v_add_f32_e32 v45, v82, v38
	ds_bpermute_b32 v44, v63, v41
	ds_bpermute_b32 v46, v61, v45
	s_waitcnt lgkmcnt(3)
	v_add_f32_e32 v67, v81, v67
	s_waitcnt lgkmcnt(2)
	v_add_f32_e32 v38, v39, v40
	ds_bpermute_b32 v68, v61, v67
	s_waitcnt lgkmcnt(2)
	v_add_f32_e32 v40, v41, v44
	s_waitcnt lgkmcnt(1)
	v_add_f32_e32 v44, v45, v46
	ds_bpermute_b32 v41, v62, v83
	ds_bpermute_b32 v45, v60, v44
	ds_bpermute_b32 v46, v62, v79
	ds_bpermute_b32 v47, v64, v40
	s_waitcnt lgkmcnt(4)
	v_add_f32_e32 v67, v67, v68
	s_waitcnt lgkmcnt(3)
	v_add_f32_e32 v41, v83, v41
	s_waitcnt lgkmcnt(2)
	v_add_f32_e32 v44, v44, v45
	s_waitcnt lgkmcnt(1)
	v_add_f32_e32 v45, v79, v46
	ds_bpermute_b32 v48, v61, v41
	ds_bpermute_b32 v46, v61, v45
	ds_bpermute_b32 v49, v63, v44
	s_waitcnt lgkmcnt(3)
	v_add_f32_e32 v40, v40, v47
	ds_bpermute_b32 v68, v60, v67
	s_waitcnt lgkmcnt(3)
	v_add_f32_e32 v41, v41, v48
	s_waitcnt lgkmcnt(2)
	v_add_f32_e32 v45, v45, v46
	ds_bpermute_b32 v48, v60, v41
	ds_bpermute_b32 v46, v60, v45
	s_waitcnt lgkmcnt(3)
	v_add_f32_e32 v44, v44, v49
	ds_bpermute_b32 v49, v64, v44
	ds_bpermute_b32 v39, v65, v38
	s_waitcnt lgkmcnt(3)
	v_add_f32_e32 v47, v41, v48
	s_waitcnt lgkmcnt(2)
	v_add_f32_e32 v45, v45, v46
	ds_bpermute_b32 v48, v63, v47
	ds_bpermute_b32 v46, v63, v45
	s_waitcnt lgkmcnt(3)
	v_add_f32_e32 v44, v44, v49
	ds_bpermute_b32 v41, v65, v40
	v_cvt_pk_bf16_f32 v34, v34, v35
	s_waitcnt lgkmcnt(2)
	v_add_f32_e32 v47, v47, v48
	s_waitcnt lgkmcnt(1)
	v_add_f32_e32 v49, v45, v46
	ds_bpermute_b32 v48, v64, v47
	ds_bpermute_b32 v66, v64, v49
	ds_bpermute_b32 v46, v65, v44
	v_cvt_pk_bf16_f32 v35, v36, v37
	global_store_dwordx2 v[56:57], v[42:43], off offset:1024
	s_waitcnt lgkmcnt(2)
	v_add_f32_e32 v45, v47, v48
	s_waitcnt lgkmcnt(1)
	v_add_f32_e32 v48, v49, v66
	ds_bpermute_b32 v66, v62, v84
	ds_bpermute_b32 v62, v62, v85
	ds_bpermute_b32 v47, v65, v45
	ds_bpermute_b32 v49, v65, v48
	global_store_dwordx2 v[56:57], v[34:35], off offset:1536
	s_waitcnt lgkmcnt(3)
	v_add_f32_e32 v66, v84, v66
	s_waitcnt lgkmcnt(2)
	v_add_f32_e32 v62, v85, v62
	ds_bpermute_b32 v69, v61, v66
	ds_bpermute_b32 v61, v61, v62
	s_waitcnt lgkmcnt(1)
	v_add_f32_e32 v66, v66, v69
	s_waitcnt lgkmcnt(0)
	v_add_f32_e32 v61, v62, v61
	ds_bpermute_b32 v69, v60, v66
	ds_bpermute_b32 v60, v60, v61
	v_add_f32_e32 v62, v67, v68
	ds_bpermute_b32 v67, v63, v62
	s_waitcnt lgkmcnt(2)
	v_add_f32_e32 v66, v66, v69
	s_waitcnt lgkmcnt(1)
	v_add_f32_e32 v60, v61, v60
	ds_bpermute_b32 v68, v63, v66
	ds_bpermute_b32 v61, v63, v60
	s_waitcnt lgkmcnt(2)
	v_add_f32_e32 v62, v62, v67
	ds_bpermute_b32 v63, v64, v62
	s_waitcnt lgkmcnt(2)
	v_add_f32_e32 v66, v66, v68
	s_waitcnt lgkmcnt(1)
	v_add_f32_e32 v68, v60, v61
	ds_bpermute_b32 v67, v64, v66
	ds_bpermute_b32 v69, v64, v68
	s_waitcnt lgkmcnt(2)
	v_add_f32_e32 v60, v62, v63
	ds_bpermute_b32 v63, v65, v60
	s_waitcnt lgkmcnt(2)
	v_add_f32_e32 v61, v66, v67
	s_waitcnt lgkmcnt(1)
	v_add_f32_e32 v62, v68, v69
	ds_bpermute_b32 v64, v65, v61
	ds_bpermute_b32 v65, v65, v62
	s_and_saveexec_b64 s[28:29], s[42:43]
	s_cbranch_execz .Lx2_777
	v_readlane_b32 s22, v255, 38
	v_readlane_b32 s23, v255, 39
	v_cndmask_b32_e64 v36, 0, v59, s[44:45]
	s_nop 0
	v_lshl_add_u64 v[34:35], s[22:23], 0, v[52:53]
	global_store_dword v[34:35], v36, off

.Lx2_774:
	s_or_b64 exec, exec, s[28:29]
	v_readlane_b32 s22, v254, 51
	s_waitcnt vmcnt(10)
	v_readlane_b32 s23, v254, 52
	v_mov_b64_e32 v[36:37], v[158:159]
	v_mov_b64_e32 v[40:41], v[154:155]
	v_mov_b64_e32 v[44:45], v[150:151]
	v_mov_b64_e32 v[48:49], v[146:147]
	v_lshl_add_u64 v[52:53], v[52:53], 0, s[22:23]
	v_lshl_add_u64 v[54:55], v[54:55], 0, s[64:65]
	s_and_b64 vcc, exec, s[16:17]
	v_mov_b64_e32 v[34:35], v[156:157]
	v_mov_b64_e32 v[38:39], v[152:153]
	v_mov_b64_e32 v[42:43], v[148:149]
	v_mov_b64_e32 v[46:47], v[144:145]
	s_mov_b32 s1, s4
	s_cbranch_vccnz .LBB0_779
	s_branch .LBB0_775
.LBB0_775:
	v_pk_mul_f32 v[128:129], v[48:49], v[48:49]
	v_pk_mul_f32 v[130:131], v[46:47], v[46:47]
	v_cmp_lt_i32_e32 vcc, v250, v213
	v_pk_mov_b32 v[132:133], v[130:131], v[128:129] op_sel:[1,0]
	v_mov_b32_e32 v131, v129
	v_pk_add_f32 v[128:129], v[132:133], v[130:131]
	v_pk_mul_f32 v[130:131], v[44:45], v[44:45]
	v_pk_add_f32 v[128:129], v[128:129], v[128:129] op_sel_hi:[0,1]
	v_pk_mul_f32 v[132:133], v[42:43], v[42:43]
	v_mul_f32_e32 v128, v38, v38
	v_pk_mov_b32 v[134:135], v[132:133], v[130:131] op_sel:[1,0]
	v_mov_b32_e32 v133, v131
	v_pk_add_f32 v[130:131], v[134:135], v[132:133]
	v_pk_fma_f32 v[132:133], v[38:39], v[38:39], v[128:129] op_sel_hi:[1,1,0]
	v_mul_f32_e32 v128, v40, v40
	v_pk_add_f32 v[130:131], v[130:131], v[130:131] op_sel_hi:[0,1]
	v_pk_fma_f32 v[134:135], v[40:41], v[40:41], v[128:129] op_sel_hi:[1,1,0]
	v_mul_f32_e32 v132, v34, v34
	v_mul_f32_e32 v134, v35, v35
	v_mul_f32_e32 v130, v36, v36
	v_mul_f32_e32 v128, v37, v37
	v_pk_add_f32 v[132:133], v[132:133], v[134:135]
	v_pk_add_f32 v[128:129], v[130:131], v[128:129]
	v_readlane_b32 s4, v254, 49
	v_pk_add_f32 v[128:129], v[132:133], v[128:129]
	s_add_i32 s4, s1, s4
	v_add_f32_e32 v128, v128, v129
	v_cndmask_b32_e32 v129, v211, v250, vcc
	v_lshlrev_b32_e32 v62, 2, v129
	ds_bpermute_b32 v129, v62, v128
	v_cmp_lt_i32_e32 vcc, v221, v213
	s_cmpk_gt_i32 s4, 0x3fff
	s_cselect_b64 s[16:17], -1, 0
	v_readlane_b32 s22, v254, 49
	s_nop 0
	s_add_i32 s22, s4, s22
	s_cmpk_lt_i32 s22, 0x4000
	s_waitcnt lgkmcnt(0)
	v_add_f32_e32 v128, v128, v129
	v_cndmask_b32_e32 v129, v211, v221, vcc
	v_lshlrev_b32_e32 v61, 2, v129
	ds_bpermute_b32 v129, v61, v128
	v_cmp_lt_i32_e32 vcc, v212, v213
	s_cselect_b32 s22, s22, s1
	s_ashr_i32 s23, s22, 31
	s_lshl_b64 s[22:23], s[22:23], 12
	s_waitcnt lgkmcnt(0)
	v_add_f32_e32 v128, v128, v129
	v_cndmask_b32_e32 v129, v211, v212, vcc
	v_lshlrev_b32_e32 v60, 2, v129
	ds_bpermute_b32 v129, v60, v128
	v_cmp_lt_i32_e32 vcc, v210, v213
	v_lshl_add_u64 v[140:141], v[50:51], 0, s[22:23]
	s_mov_b64 s[22:23], 0x400
	v_lshl_add_u64 v[132:133], v[140:141], 0, s[22:23]
	s_waitcnt lgkmcnt(0)
	v_add_f32_e32 v128, v128, v129
	v_cndmask_b32_e32 v129, v211, v210, vcc
	v_lshlrev_b32_e32 v63, 2, v129
	ds_bpermute_b32 v129, v63, v128
	v_cmp_lt_i32_e32 vcc, v218, v213
	s_mov_b64 s[22:23], 0x800
	v_add_u32_e32 v70, 0x12000, v58
	v_readlane_b32 s5, v254, 50
	s_waitcnt lgkmcnt(0)
	v_add_f32_e32 v136, v128, v129
	v_cndmask_b32_e32 v128, v211, v218, vcc
	v_lshlrev_b32_e32 v64, 2, v128
	ds_bpermute_b32 v137, v64, v136
	v_cmp_lt_i32_e32 vcc, v219, v213
	global_load_dwordx4 v[144:147], v[140:141], off
	global_load_dwordx4 v[148:151], v[132:133], off
	s_brev_b32 s5, 32
	s_waitcnt lgkmcnt(0)
	v_add_f32_e32 v56, v136, v137
	v_cndmask_b32_e32 v136, v211, v219, vcc
	v_lshlrev_b32_e32 v65, 2, v136
	ds_bpermute_b32 v57, v65, v56
	v_lshl_add_u64 v[136:137], v[140:141], 0, s[22:23]
	s_mov_b64 s[22:23], 0xc00
	v_lshl_add_u64 v[140:141], v[140:141], 0, s[22:23]
	global_load_dwordx4 v[152:155], v[136:137], off
	global_load_dwordx4 v[156:159], v[140:141], off
	v_readlane_b32 s22, v255, 38
	ds_read_b128 v[66:69], v70
	ds_read_b128 v[70:73], v70 offset:16
	v_readlane_b32 s23, v255, 39
	s_waitcnt lgkmcnt(2)
	v_add_f32_e32 v59, v56, v57
	v_cvt_pk_bf16_f32 v74, v46, v47
	v_lshl_add_u64 v[56:57], s[22:23], 0, v[54:55]
	v_add_co_u32_e32 v56, vcc, s5, v56
	v_cvt_pk_bf16_f32 v75, v48, v49
	s_nop 0
	v_addc_co_u32_e32 v57, vcc, 0, v57, vcc
	v_mul_f32_e32 v46, v14, v46
	global_store_dwordx2 v[56:57], v[74:75], off
	s_waitcnt lgkmcnt(0)
	v_fma_f32 v79, v46, v70, 0
	v_add_u32_e32 v70, 0x12800, v58
	v_fma_f32 v78, v46, v66, 0
	v_fma_f32 v80, v46, v67, 0
	v_fma_f32 v82, v46, v68, 0
	v_fma_f32 v83, v46, v69, 0
	ds_read_b128 v[66:69], v70
	ds_read_b128 v[74:77], v70 offset:16
	v_fma_f32 v81, v46, v71, 0
	v_fma_f32 v84, v46, v72, 0
	v_fma_f32 v85, v46, v73, 0
	v_mul_f32_e32 v46, v15, v47
	v_add_u32_e32 v47, 0x13000, v58
	s_waitcnt lgkmcnt(1)
	v_fmac_f32_e32 v78, v46, v66
	v_fmac_f32_e32 v80, v46, v67
	v_fmac_f32_e32 v82, v46, v68
	v_fmac_f32_e32 v83, v46, v69
	ds_read_b128 v[66:69], v47
	ds_read_b128 v[70:73], v47 offset:16
	s_waitcnt lgkmcnt(2)
	v_fmac_f32_e32 v79, v46, v74
	v_fmac_f32_e32 v81, v46, v75
	v_fmac_f32_e32 v84, v46, v76
	v_fmac_f32_e32 v85, v46, v77
	v_mul_f32_e32 v46, v16, v48
	v_add_u32_e32 v47, 0x13800, v58
	s_waitcnt lgkmcnt(1)
	v_fmac_f32_e32 v78, v46, v66
	v_fmac_f32_e32 v80, v46, v67
	v_fmac_f32_e32 v82, v46, v68
	v_fmac_f32_e32 v83, v46, v69
	ds_read_b128 v[66:69], v47
	ds_read_b128 v[74:77], v47 offset:16
	s_waitcnt lgkmcnt(2)
	v_fmac_f32_e32 v79, v46, v70
	v_fmac_f32_e32 v81, v46, v71
	v_fmac_f32_e32 v84, v46, v72
	v_fmac_f32_e32 v85, v46, v73
	v_mul_f32_e32 v46, v17, v49
	s_waitcnt lgkmcnt(1)
	v_fmac_f32_e32 v78, v46, v66
	v_add_u32_e32 v66, 0x14000, v58
	s_waitcnt lgkmcnt(0)
	v_fmac_f32_e32 v79, v46, v74
	v_fmac_f32_e32 v80, v46, v67
	v_fmac_f32_e32 v81, v46, v75
	v_fmac_f32_e32 v82, v46, v68
	v_fmac_f32_e32 v84, v46, v76
	v_fmac_f32_e32 v83, v46, v69
	v_fmac_f32_e32 v85, v46, v77
	ds_read_b128 v[46:49], v66
	ds_read_b128 v[66:69], v66 offset:16
	v_cvt_pk_bf16_f32 v70, v42, v43
	v_cvt_pk_bf16_f32 v71, v44, v45
	v_mul_f32_e32 v42, v10, v42
	global_store_dwordx2 v[56:57], v[70:71], off offset:512
	s_waitcnt lgkmcnt(1)
	v_fmac_f32_e32 v78, v42, v46
	v_add_u32_e32 v46, 0x14800, v58
	ds_read_b128 v[70:73], v46
	ds_read_b128 v[74:77], v46 offset:16
	s_waitcnt lgkmcnt(2)
	v_fmac_f32_e32 v79, v42, v66
	v_fmac_f32_e32 v80, v42, v47
	v_fmac_f32_e32 v81, v42, v67
	v_fmac_f32_e32 v82, v42, v48
	v_fmac_f32_e32 v84, v42, v68
	v_fmac_f32_e32 v83, v42, v49
	v_fmac_f32_e32 v85, v42, v69
	v_mul_f32_e32 v42, v11, v43
	v_add_u32_e32 v43, 0x15000, v58
	ds_read_b128 v[46:49], v43
	ds_read_b128 v[66:69], v43 offset:16
	v_add_u32_e32 v43, 0x15800, v58
	s_waitcnt lgkmcnt(3)
	v_fmac_f32_e32 v78, v42, v70
	s_waitcnt lgkmcnt(2)
	v_fmac_f32_e32 v79, v42, v74
	v_fmac_f32_e32 v80, v42, v71
	v_fmac_f32_e32 v81, v42, v75
	v_fmac_f32_e32 v82, v42, v72
	v_fmac_f32_e32 v84, v42, v76
	v_fmac_f32_e32 v83, v42, v73
	v_fmac_f32_e32 v85, v42, v77
	ds_read_b128 v[70:73], v43
	ds_read_b128 v[74:77], v43 offset:16
	v_mul_f32_e32 v42, v12, v44
	s_waitcnt lgkmcnt(3)
	v_fmac_f32_e32 v78, v42, v46
	s_waitcnt lgkmcnt(2)
	v_fmac_f32_e32 v79, v42, v66
	v_fmac_f32_e32 v80, v42, v47
	v_fmac_f32_e32 v81, v42, v67
	v_fmac_f32_e32 v82, v42, v48
	v_fmac_f32_e32 v84, v42, v68
	v_fmac_f32_e32 v83, v42, v49
	v_fmac_f32_e32 v85, v42, v69
	v_mul_f32_e32 v42, v13, v45
	s_waitcnt lgkmcnt(1)
	v_fmac_f32_e32 v78, v42, v70
	s_waitcnt lgkmcnt(0)
	v_fmac_f32_e32 v79, v42, v74
	v_fmac_f32_e32 v80, v42, v71
	v_fmac_f32_e32 v81, v42, v75
	v_fmac_f32_e32 v82, v42, v72
	v_fmac_f32_e32 v84, v42, v76
	v_fmac_f32_e32 v83, v42, v73
	v_fmac_f32_e32 v85, v42, v77
	v_add_u32_e32 v42, 0x16000, v58
	ds_read_b128 v[44:47], v42
	ds_read_b128 v[66:69], v42 offset:16
	v_cvt_pk_bf16_f32 v42, v38, v39
	v_mul_f32_e32 v38, v6, v38
	v_cvt_pk_bf16_f32 v43, v40, v41
	s_waitcnt lgkmcnt(1)
	v_fmac_f32_e32 v78, v38, v44
	v_add_u32_e32 v44, 0x16800, v58
	ds_read_b128 v[70:73], v44
	ds_read_b128 v[74:77], v44 offset:16
	s_waitcnt lgkmcnt(2)
	v_fmac_f32_e32 v79, v38, v66
	v_fmac_f32_e32 v80, v38, v45
	v_fmac_f32_e32 v81, v38, v67
	v_fmac_f32_e32 v82, v38, v46
	v_fmac_f32_e32 v84, v38, v68
	v_fmac_f32_e32 v83, v38, v47
	v_fmac_f32_e32 v85, v38, v69
	v_mul_f32_e32 v38, v7, v39
	v_add_u32_e32 v39, 0x17000, v58
	ds_read_b128 v[44:47], v39
	ds_read_b128 v[66:69], v39 offset:16
	v_add_u32_e32 v39, 0x17800, v58
	s_waitcnt lgkmcnt(3)
	v_fmac_f32_e32 v78, v38, v70
	s_waitcnt lgkmcnt(2)
	v_fmac_f32_e32 v79, v38, v74
	v_fmac_f32_e32 v80, v38, v71
	v_fmac_f32_e32 v81, v38, v75
	v_fmac_f32_e32 v82, v38, v72
	v_fmac_f32_e32 v84, v38, v76
	v_fmac_f32_e32 v83, v38, v73
	v_fmac_f32_e32 v85, v38, v77
	v_mul_f32_e32 v38, v8, v40
	ds_read_b128 v[70:73], v39
	ds_read_b128 v[74:77], v39 offset:16
	s_waitcnt lgkmcnt(3)
	v_fmac_f32_e32 v78, v38, v44
	v_add_u32_e32 v44, 0x18000, v58
	s_waitcnt lgkmcnt(2)
	v_fmac_f32_e32 v79, v38, v66
	v_fmac_f32_e32 v80, v38, v45
	v_fmac_f32_e32 v81, v38, v67
	v_fmac_f32_e32 v82, v38, v46
	v_fmac_f32_e32 v84, v38, v68
	v_fmac_f32_e32 v83, v38, v47
	v_fmac_f32_e32 v85, v38, v69
	v_mul_f32_e32 v48, v9, v41
	ds_read_b128 v[38:41], v44
	ds_read_b128 v[44:47], v44 offset:16
	s_waitcnt lgkmcnt(3)
	v_fmac_f32_e32 v78, v48, v70
	s_waitcnt lgkmcnt(2)
	v_fmac_f32_e32 v79, v48, v74
	v_fmac_f32_e32 v80, v48, v71
	v_fmac_f32_e32 v81, v48, v75
	v_fmac_f32_e32 v82, v48, v72
	v_fmac_f32_e32 v84, v48, v76
	v_fmac_f32_e32 v83, v48, v73
	v_fmac_f32_e32 v85, v48, v77
	v_mul_f32_e32 v48, v2, v34
	s_waitcnt lgkmcnt(1)
	v_fmac_f32_e32 v78, v48, v38
	v_add_u32_e32 v38, 0x18800, v58
	ds_read_b128 v[66:69], v38
	ds_read_b128 v[70:73], v38 offset:16
	s_waitcnt lgkmcnt(2)
	v_fmac_f32_e32 v79, v48, v44
	v_add_u32_e32 v44, 0x19000, v58
	v_fmac_f32_e32 v80, v48, v39
	v_fmac_f32_e32 v81, v48, v45
	v_fmac_f32_e32 v82, v48, v40
	v_fmac_f32_e32 v84, v48, v46
	v_fmac_f32_e32 v83, v48, v41
	v_fmac_f32_e32 v85, v48, v47
	ds_read_b128 v[38:41], v44
	ds_read_b128 v[44:47], v44 offset:16
	v_mul_f32_e32 v48, v3, v35
	s_waitcnt lgkmcnt(3)
	v_fmac_f32_e32 v78, v48, v66
	s_waitcnt lgkmcnt(2)
	v_fmac_f32_e32 v79, v48, v70
	v_fmac_f32_e32 v80, v48, v67
	v_fmac_f32_e32 v81, v48, v71
	v_fmac_f32_e32 v82, v48, v68
	v_fmac_f32_e32 v84, v48, v72
	v_fmac_f32_e32 v83, v48, v69
	v_fmac_f32_e32 v85, v48, v73
	v_mul_f32_e32 v48, v4, v36
	s_waitcnt lgkmcnt(1)
	v_fmac_f32_e32 v78, v48, v38
	v_add_u32_e32 v38, 0x19800, v58
	ds_read_b128 v[66:69], v38
	ds_read_b128 v[70:73], v38 offset:16
	v_mul_f32_e32 v38, v5, v37
	v_fmac_f32_e32 v80, v48, v39
	v_fmac_f32_e32 v82, v48, v40
	s_waitcnt lgkmcnt(1)
	v_fmac_f32_e32 v78, v38, v66
	ds_bpermute_b32 v39, v62, v78
	v_fmac_f32_e32 v80, v38, v67
	v_fmac_f32_e32 v83, v48, v41
	ds_bpermute_b32 v41, v62, v80
	v_fmac_f32_e32 v79, v48, v44
	s_waitcnt lgkmcnt(1)
	v_add_f32_e32 v39, v78, v39
	ds_bpermute_b32 v40, v61, v39
	v_fmac_f32_e32 v81, v48, v45
	s_waitcnt lgkmcnt(1)
	v_add_f32_e32 v41, v80, v41
	ds_bpermute_b32 v44, v61, v41
	v_fmac_f32_e32 v84, v48, v46
	s_waitcnt lgkmcnt(1)
	v_add_f32_e32 v39, v39, v40
	ds_bpermute_b32 v40, v60, v39
	v_fmac_f32_e32 v85, v48, v47
	v_fmac_f32_e32 v82, v38, v68
	s_waitcnt lgkmcnt(1)
	v_add_f32_e32 v41, v41, v44
	v_fmac_f32_e32 v79, v38, v70
	s_waitcnt lgkmcnt(0)
	v_add_f32_e32 v39, v39, v40
	v_fmac_f32_e32 v81, v38, v71
	v_fmac_f32_e32 v84, v38, v72
	v_fmac_f32_e32 v83, v38, v69
	ds_bpermute_b32 v40, v63, v39
	ds_bpermute_b32 v44, v60, v41
	v_fmac_f32_e32 v85, v38, v73
	ds_bpermute_b32 v38, v62, v82
	ds_bpermute_b32 v67, v62, v81
	s_waitcnt lgkmcnt(3)
	v_add_f32_e32 v39, v39, v40
	s_waitcnt lgkmcnt(2)
	v_add_f32_e32 v41, v41, v44
	ds_bpermute_b32 v40, v64, v39
	s_waitcnt lgkmcnt(2)
	v_add_f32_e32 v45, v82, v38
	ds_bpermute_b32 v44, v63, v41
	ds_bpermute_b32 v46, v61, v45
	s_waitcnt lgkmcnt(3)
	v_add_f32_e32 v67, v81, v67
	s_waitcnt lgkmcnt(2)
	v_add_f32_e32 v38, v39, v40
	ds_bpermute_b32 v68, v61, v67
	s_waitcnt lgkmcnt(2)
	v_add_f32_e32 v40, v41, v44
	s_waitcnt lgkmcnt(1)
	v_add_f32_e32 v44, v45, v46
	ds_bpermute_b32 v41, v62, v83
	ds_bpermute_b32 v45, v60, v44
	ds_bpermute_b32 v46, v62, v79
	ds_bpermute_b32 v47, v64, v40
	s_waitcnt lgkmcnt(4)
	v_add_f32_e32 v67, v67, v68
	s_waitcnt lgkmcnt(3)
	v_add_f32_e32 v41, v83, v41
	s_waitcnt lgkmcnt(2)
	v_add_f32_e32 v44, v44, v45
	s_waitcnt lgkmcnt(1)
	v_add_f32_e32 v45, v79, v46
	ds_bpermute_b32 v48, v61, v41
	ds_bpermute_b32 v46, v61, v45
	ds_bpermute_b32 v49, v63, v44
	s_waitcnt lgkmcnt(3)
	v_add_f32_e32 v40, v40, v47
	ds_bpermute_b32 v68, v60, v67
	s_waitcnt lgkmcnt(3)
	v_add_f32_e32 v41, v41, v48
	s_waitcnt lgkmcnt(2)
	v_add_f32_e32 v45, v45, v46
	ds_bpermute_b32 v48, v60, v41
	ds_bpermute_b32 v46, v60, v45
	s_waitcnt lgkmcnt(3)
	v_add_f32_e32 v44, v44, v49
	ds_bpermute_b32 v49, v64, v44
	ds_bpermute_b32 v39, v65, v38
	s_waitcnt lgkmcnt(3)
	v_add_f32_e32 v47, v41, v48
	s_waitcnt lgkmcnt(2)
	v_add_f32_e32 v45, v45, v46
	ds_bpermute_b32 v48, v63, v47
	ds_bpermute_b32 v46, v63, v45
	s_waitcnt lgkmcnt(3)
	v_add_f32_e32 v44, v44, v49
	ds_bpermute_b32 v41, v65, v40
	v_cvt_pk_bf16_f32 v34, v34, v35
	s_waitcnt lgkmcnt(2)
	v_add_f32_e32 v47, v47, v48
	s_waitcnt lgkmcnt(1)
	v_add_f32_e32 v49, v45, v46
	ds_bpermute_b32 v48, v64, v47
	ds_bpermute_b32 v66, v64, v49
	ds_bpermute_b32 v46, v65, v44
	v_cvt_pk_bf16_f32 v35, v36, v37
	global_store_dwordx2 v[56:57], v[42:43], off offset:1024
	s_waitcnt lgkmcnt(2)
	v_add_f32_e32 v45, v47, v48
	s_waitcnt lgkmcnt(1)
	v_add_f32_e32 v48, v49, v66
	ds_bpermute_b32 v66, v62, v84
	ds_bpermute_b32 v62, v62, v85
	ds_bpermute_b32 v47, v65, v45
	ds_bpermute_b32 v49, v65, v48
	global_store_dwordx2 v[56:57], v[34:35], off offset:1536
	s_waitcnt lgkmcnt(3)
	v_add_f32_e32 v66, v84, v66
	s_waitcnt lgkmcnt(2)
	v_add_f32_e32 v62, v85, v62
	ds_bpermute_b32 v69, v61, v66
	ds_bpermute_b32 v61, v61, v62
	s_waitcnt lgkmcnt(1)
	v_add_f32_e32 v66, v66, v69
	s_waitcnt lgkmcnt(0)
	v_add_f32_e32 v61, v62, v61
	ds_bpermute_b32 v69, v60, v66
	ds_bpermute_b32 v60, v60, v61
	v_add_f32_e32 v62, v67, v68
	ds_bpermute_b32 v67, v63, v62
	s_waitcnt lgkmcnt(2)
	v_add_f32_e32 v66, v66, v69
	s_waitcnt lgkmcnt(1)
	v_add_f32_e32 v60, v61, v60
	ds_bpermute_b32 v68, v63, v66
	ds_bpermute_b32 v61, v63, v60
	s_waitcnt lgkmcnt(2)
	v_add_f32_e32 v62, v62, v67
	ds_bpermute_b32 v63, v64, v62
	s_waitcnt lgkmcnt(2)
	v_add_f32_e32 v66, v66, v68
	s_waitcnt lgkmcnt(1)
	v_add_f32_e32 v68, v60, v61
	ds_bpermute_b32 v67, v64, v66
	ds_bpermute_b32 v69, v64, v68
	s_waitcnt lgkmcnt(2)
	v_add_f32_e32 v60, v62, v63
	ds_bpermute_b32 v63, v65, v60
	s_waitcnt lgkmcnt(2)
	v_add_f32_e32 v61, v66, v67
	s_waitcnt lgkmcnt(1)
	v_add_f32_e32 v62, v68, v69
	ds_bpermute_b32 v64, v65, v61
	ds_bpermute_b32 v65, v65, v62
	s_and_saveexec_b64 s[28:29], s[42:43]
	s_cbranch_execz .LBB0_777
	v_readlane_b32 s22, v255, 38
	v_readlane_b32 s23, v255, 39
	v_cndmask_b32_e64 v36, 0, v59, s[44:45]
	s_nop 0
	v_lshl_add_u64 v[34:35], s[22:23], 0, v[52:53]
	global_store_dword v[34:35], v36, off

.LBB0_779:
	s_waitcnt vmcnt(0)
	v_readlane_b32 s9, v255, 28
	v_readlane_b32 s64, v255, 29
	v_readlane_b32 s65, v255, 30
	v_readlane_b32 s66, v255, 31
